# baseline (speedup 1.0000x reference)
; __device__ __forceinline__ float bf_lo(u32 v) { return __uint_as_float(v << 16); }
; __device__ __forceinline__ float bf_hi(u32 v) { return __uint_as_float(v & 0xffff0000u); }
; __device__ __forceinline__ void gemm_tile(const TileDesc& td, char* shm_c, const int wv) {
;     ...
;   } else {
;     #pragma unroll
;     for (int ai = 0; ai < 2; ++ai)
;     #pragma unroll
;     for (int m = 0; m < 4; ++m) {
;       int f0 = td.brow + ai * 128 + m * 16 + ar_l;
;       float4 ps = *(const float4*)(td.aux + f0);
;       #pragma unroll
;       for (int bj = 0; bj < 2; ++bj)
;       #pragma unroll
;       for (int n = 0; n < 2; ++n) {
;         long o = (long)(td.bcol + bj * 128 + n * 16 + br_l) * td.ldo + f0;
;         uint2 g = *(const uint2*)(td.outb + o);
;         f32x4 v = acc[ai][bj][m][n];
;         uint2 pk;
;         pk.x = pack2(v[0] * ps.x * bf_lo(g.x), v[1] * ps.y * bf_hi(g.x));
;         pk.y = pack2(v[2] * ps.z * bf_lo(g.y), v[3] * ps.w * bf_hi(g.y));
;         *(uint2*)(td.outb + o) = pk;
;       }
;     }
.LBB0_482:
	s_lshl_b64 s[28:29], s[28:29], 2
	v_mbcnt_lo_u32_b32 v128, -1, 0
	v_mbcnt_hi_u32_b32 v128, -1, v128
	s_add_u32 s28, s80, s28
	v_lshrrev_b32_e32 v130, 2, v128
	v_and_or_b32 v130, v130, 12, s40
	v_and_or_b32 v131, v128, 15, s44
	s_addc_u32 s29, s81, s29
	v_lshl_add_u32 v128, s63, 8, v130
	v_lshl_or_b32 v130, s62, 7, v131
	s_add_u32 s26, s38, s26
	v_mul_u32_u24_e32 v130, 0x2800, v130
	s_addc_u32 s27, s39, s27
	v_lshlrev_b32_e32 v130, 1, v130
	v_mov_b32_e32 v131, v129
	v_lshl_add_u64 v[132:133], v[128:129], 2, s[28:29]
	v_lshl_add_u64 v[136:137], s[26:27], 0, v[130:131]
	v_lshlrev_b32_e32 v128, 1, v128
	s_mov_b64 s[26:27], 0x50000
	v_lshl_add_u64 v[130:131], v[136:137], 0, v[128:129]
	v_lshl_add_u64 v[138:139], v[136:137], 0, s[26:27]
	s_mov_b64 s[26:27], 0x280000
	v_add_co_u32_e32 v134, vcc, 0x50000, v130
	s_nop 1
	v_addc_co_u32_e32 v135, vcc, 0, v131, vcc
	v_add_co_u32_e32 v136, vcc, 0x280000, v130
	s_nop 1
	v_addc_co_u32_e32 v137, vcc, 0, v131, vcc
	v_add_co_u32_e32 v138, vcc, 0x2d0000, v130
	s_nop 1
	v_addc_co_u32_e32 v139, vcc, 0, v131, vcc
	s_mov_b64 s[26:27], 0x2d0000
	global_load_dwordx4 v[144:147], v[132:133], off
	global_load_dwordx4 v[148:151], v[132:133], off offset:64
	global_load_dwordx4 v[152:155], v[132:133], off offset:128
	global_load_dwordx4 v[156:159], v[132:133], off offset:192
	global_load_dwordx4 v[160:163], v[132:133], off offset:512
	global_load_dwordx4 v[164:167], v[132:133], off offset:576
	global_load_dwordx4 v[168:171], v[132:133], off offset:640
	global_load_dwordx4 v[172:175], v[132:133], off offset:704
	global_load_dwordx2 v[176:177], v[130:131], off
	global_load_dwordx2 v[178:179], v[134:135], off
	global_load_dwordx2 v[180:181], v[136:137], off
	global_load_dwordx2 v[182:183], v[138:139], off
	global_load_dwordx2 v[184:185], v[130:131], off offset:32
	global_load_dwordx2 v[186:187], v[134:135], off offset:32
	global_load_dwordx2 v[188:189], v[136:137], off offset:32
	global_load_dwordx2 v[190:191], v[138:139], off offset:32
	global_load_dwordx2 v[192:193], v[130:131], off offset:64
	global_load_dwordx2 v[194:195], v[134:135], off offset:64
	global_load_dwordx2 v[196:197], v[136:137], off offset:64
	global_load_dwordx2 v[198:199], v[138:139], off offset:64
	global_load_dwordx2 v[200:201], v[130:131], off offset:96
	global_load_dwordx2 v[202:203], v[134:135], off offset:96
	global_load_dwordx2 v[204:205], v[136:137], off offset:96
	global_load_dwordx2 v[206:207], v[138:139], off offset:96
	global_load_dwordx2 v[208:209], v[130:131], off offset:256
	global_load_dwordx2 v[210:211], v[134:135], off offset:256
	global_load_dwordx2 v[212:213], v[136:137], off offset:256
	global_load_dwordx2 v[214:215], v[138:139], off offset:256
	global_load_dwordx2 v[216:217], v[130:131], off offset:288
	global_load_dwordx2 v[218:219], v[134:135], off offset:288
	global_load_dwordx2 v[220:221], v[136:137], off offset:288
	global_load_dwordx2 v[222:223], v[138:139], off offset:288
	global_load_dwordx2 v[224:225], v[130:131], off offset:320
	global_load_dwordx2 v[226:227], v[134:135], off offset:320
	global_load_dwordx2 v[228:229], v[136:137], off offset:320
	global_load_dwordx2 v[230:231], v[138:139], off offset:320
	global_load_dwordx2 v[232:233], v[130:131], off offset:352
	global_load_dwordx2 v[234:235], v[134:135], off offset:352
	global_load_dwordx2 v[236:237], v[136:137], off offset:352
	global_load_dwordx2 v[238:239], v[138:139], off offset:352
	s_add_i32 s61, s61, s91
	s_add_i32 s53, s53, s54
	s_cmpk_lt_i32 s61, 0x200
	v_readlane_b32 s67, v255, 34
	s_waitcnt vmcnt(31)
	v_pk_mul_f32 v[112:113], v[112:113], v[144:145]
	v_pk_mul_f32 v[114:115], v[114:115], v[146:147]
	v_lshlrev_b32_e32 v240, 16, v176
	v_and_b32_e32 v241, 0xffff0000, v176
	v_lshlrev_b32_e32 v242, 16, v177
	v_and_b32_e32 v243, 0xffff0000, v177
	v_pk_mul_f32 v[112:113], v[112:113], v[240:241]
	v_pk_mul_f32 v[114:115], v[114:115], v[242:243]
	v_cvt_pk_bf16_f32 v112, v112, v113
	v_cvt_pk_bf16_f32 v113, v114, v115
	global_store_dwordx2 v[130:131], v[112:113], off
	s_waitcnt vmcnt(31)
	v_pk_mul_f32 v[116:117], v[116:117], v[144:145]
	v_pk_mul_f32 v[118:119], v[118:119], v[146:147]
	v_lshlrev_b32_e32 v240, 16, v178
	v_and_b32_e32 v241, 0xffff0000, v178
	v_lshlrev_b32_e32 v242, 16, v179
	v_and_b32_e32 v243, 0xffff0000, v179
	v_pk_mul_f32 v[116:117], v[116:117], v[240:241]
	v_pk_mul_f32 v[118:119], v[118:119], v[242:243]
	v_cvt_pk_bf16_f32 v116, v116, v117
	v_cvt_pk_bf16_f32 v117, v118, v119
	global_store_dwordx2 v[134:135], v[116:117], off
	s_waitcnt vmcnt(31)
	v_pk_mul_f32 v[120:121], v[120:121], v[144:145]
	v_pk_mul_f32 v[122:123], v[122:123], v[146:147]
	v_lshlrev_b32_e32 v240, 16, v180
	v_and_b32_e32 v241, 0xffff0000, v180
	v_lshlrev_b32_e32 v242, 16, v181
	v_and_b32_e32 v243, 0xffff0000, v181
	v_pk_mul_f32 v[120:121], v[120:121], v[240:241]
	v_pk_mul_f32 v[122:123], v[122:123], v[242:243]
	v_cvt_pk_bf16_f32 v120, v120, v121
	v_cvt_pk_bf16_f32 v121, v122, v123
	global_store_dwordx2 v[136:137], v[120:121], off
	s_waitcnt vmcnt(31)
	v_pk_mul_f32 v[124:125], v[124:125], v[144:145]
	v_pk_mul_f32 v[126:127], v[126:127], v[146:147]
	v_lshlrev_b32_e32 v240, 16, v182
	v_and_b32_e32 v241, 0xffff0000, v182
	v_lshlrev_b32_e32 v242, 16, v183
	v_and_b32_e32 v243, 0xffff0000, v183
	v_pk_mul_f32 v[124:125], v[124:125], v[240:241]
	v_pk_mul_f32 v[126:127], v[126:127], v[242:243]
	v_cvt_pk_bf16_f32 v124, v124, v125
	v_cvt_pk_bf16_f32 v125, v126, v127
	global_store_dwordx2 v[138:139], v[124:125], off
	s_waitcnt vmcnt(31)
; __device__ __forceinline__ float bf_lo(u32 v) { return __uint_as_float(v << 16); }
; __device__ __forceinline__ float bf_hi(u32 v) { return __uint_as_float(v & 0xffff0000u); }
; __device__ __forceinline__ void gemm_tile(const TileDesc& td, char* shm_c, const int wv) {
;     ...
;     #pragma unroll
;     for (int ai = 0; ai < 2; ++ai)
;     #pragma unroll
;     for (int m = 0; m < 4; ++m) {
;       int f0 = td.brow + ai * 128 + m * 16 + ar_l;
;       float4 ps = *(const float4*)(td.aux + f0);
;       #pragma unroll
;       for (int bj = 0; bj < 2; ++bj)
;       #pragma unroll
;       for (int n = 0; n < 2; ++n) {
;         long o = (long)(td.bcol + bj * 128 + n * 16 + br_l) * td.ldo + f0;
;         uint2 g = *(const uint2*)(td.outb + o);
;         f32x4 v = acc[ai][bj][m][n];
;         uint2 pk;
;         pk.x = pack2(v[0] * ps.x * bf_lo(g.x), v[1] * ps.y * bf_hi(g.x));
;         pk.y = pack2(v[2] * ps.z * bf_lo(g.y), v[3] * ps.w * bf_hi(g.y));
;         *(uint2*)(td.outb + o) = pk;
;       }
;     }
	v_pk_mul_f32 v[108:109], v[108:109], v[148:149]
	v_pk_mul_f32 v[110:111], v[110:111], v[150:151]
	v_lshlrev_b32_e32 v240, 16, v184
	v_and_b32_e32 v241, 0xffff0000, v184
	v_lshlrev_b32_e32 v242, 16, v185
	v_and_b32_e32 v243, 0xffff0000, v185
	v_pk_mul_f32 v[108:109], v[108:109], v[240:241]
	v_pk_mul_f32 v[110:111], v[110:111], v[242:243]
	v_cvt_pk_bf16_f32 v108, v108, v109
	v_cvt_pk_bf16_f32 v109, v110, v111
	global_store_dwordx2 v[130:131], v[108:109], off offset:32
	s_waitcnt vmcnt(31)
	v_pk_mul_f32 v[96:97], v[96:97], v[148:149]
	v_pk_mul_f32 v[98:99], v[98:99], v[150:151]
	v_lshlrev_b32_e32 v240, 16, v186
	v_and_b32_e32 v241, 0xffff0000, v186
	v_lshlrev_b32_e32 v242, 16, v187
	v_and_b32_e32 v243, 0xffff0000, v187
	v_pk_mul_f32 v[96:97], v[96:97], v[240:241]
	v_pk_mul_f32 v[98:99], v[98:99], v[242:243]
	v_cvt_pk_bf16_f32 v96, v96, v97
	v_cvt_pk_bf16_f32 v97, v98, v99
	global_store_dwordx2 v[134:135], v[96:97], off offset:32
	s_waitcnt vmcnt(31)
	v_pk_mul_f32 v[104:105], v[104:105], v[148:149]
	v_pk_mul_f32 v[106:107], v[106:107], v[150:151]
	v_lshlrev_b32_e32 v240, 16, v188
	v_and_b32_e32 v241, 0xffff0000, v188
	v_lshlrev_b32_e32 v242, 16, v189
	v_and_b32_e32 v243, 0xffff0000, v189
	v_pk_mul_f32 v[104:105], v[104:105], v[240:241]
	v_pk_mul_f32 v[106:107], v[106:107], v[242:243]
	v_cvt_pk_bf16_f32 v104, v104, v105
	v_cvt_pk_bf16_f32 v105, v106, v107
	global_store_dwordx2 v[136:137], v[104:105], off offset:32
	s_waitcnt vmcnt(31)
	v_pk_mul_f32 v[100:101], v[100:101], v[148:149]
	v_pk_mul_f32 v[102:103], v[102:103], v[150:151]
	v_lshlrev_b32_e32 v240, 16, v190
	v_and_b32_e32 v241, 0xffff0000, v190
	v_lshlrev_b32_e32 v242, 16, v191
	v_and_b32_e32 v243, 0xffff0000, v191
	v_pk_mul_f32 v[100:101], v[100:101], v[240:241]
	v_pk_mul_f32 v[102:103], v[102:103], v[242:243]
	v_cvt_pk_bf16_f32 v100, v100, v101
	v_cvt_pk_bf16_f32 v101, v102, v103
	global_store_dwordx2 v[138:139], v[100:101], off offset:32
	s_waitcnt vmcnt(31)
	v_pk_mul_f32 v[92:93], v[92:93], v[152:153]
	v_pk_mul_f32 v[94:95], v[94:95], v[154:155]
	v_lshlrev_b32_e32 v240, 16, v192
	v_and_b32_e32 v241, 0xffff0000, v192
	v_lshlrev_b32_e32 v242, 16, v193
	v_and_b32_e32 v243, 0xffff0000, v193
	v_pk_mul_f32 v[92:93], v[92:93], v[240:241]
	v_pk_mul_f32 v[94:95], v[94:95], v[242:243]
	v_cvt_pk_bf16_f32 v92, v92, v93
	v_cvt_pk_bf16_f32 v93, v94, v95
	global_store_dwordx2 v[130:131], v[92:93], off offset:64
	s_waitcnt vmcnt(31)
	v_pk_mul_f32 v[80:81], v[80:81], v[152:153]
	v_pk_mul_f32 v[82:83], v[82:83], v[154:155]
	v_lshlrev_b32_e32 v240, 16, v194
	v_and_b32_e32 v241, 0xffff0000, v194
	v_lshlrev_b32_e32 v242, 16, v195
	v_and_b32_e32 v243, 0xffff0000, v195
	v_pk_mul_f32 v[80:81], v[80:81], v[240:241]
	v_pk_mul_f32 v[82:83], v[82:83], v[242:243]
	v_cvt_pk_bf16_f32 v80, v80, v81
	v_cvt_pk_bf16_f32 v81, v82, v83
	global_store_dwordx2 v[134:135], v[80:81], off offset:64
	s_waitcnt vmcnt(31)
	v_pk_mul_f32 v[88:89], v[88:89], v[152:153]
	v_pk_mul_f32 v[90:91], v[90:91], v[154:155]
	v_lshlrev_b32_e32 v240, 16, v196
	v_and_b32_e32 v241, 0xffff0000, v196
	v_lshlrev_b32_e32 v242, 16, v197
	v_and_b32_e32 v243, 0xffff0000, v197
	v_pk_mul_f32 v[88:89], v[88:89], v[240:241]
	v_pk_mul_f32 v[90:91], v[90:91], v[242:243]
	v_cvt_pk_bf16_f32 v88, v88, v89
	v_cvt_pk_bf16_f32 v89, v90, v91
	global_store_dwordx2 v[136:137], v[88:89], off offset:64
	s_waitcnt vmcnt(31)
	v_pk_mul_f32 v[84:85], v[84:85], v[152:153]
	v_pk_mul_f32 v[86:87], v[86:87], v[154:155]
	v_lshlrev_b32_e32 v240, 16, v198
	v_and_b32_e32 v241, 0xffff0000, v198
	v_lshlrev_b32_e32 v242, 16, v199
	v_and_b32_e32 v243, 0xffff0000, v199
	v_pk_mul_f32 v[84:85], v[84:85], v[240:241]
	v_pk_mul_f32 v[86:87], v[86:87], v[242:243]
	v_cvt_pk_bf16_f32 v84, v84, v85
	v_cvt_pk_bf16_f32 v85, v86, v87
	global_store_dwordx2 v[138:139], v[84:85], off offset:64
	s_waitcnt vmcnt(31)
	v_pk_mul_f32 v[76:77], v[76:77], v[156:157]
	v_pk_mul_f32 v[78:79], v[78:79], v[158:159]
	v_lshlrev_b32_e32 v240, 16, v200
	v_and_b32_e32 v241, 0xffff0000, v200
	v_lshlrev_b32_e32 v242, 16, v201
	v_and_b32_e32 v243, 0xffff0000, v201
	v_pk_mul_f32 v[76:77], v[76:77], v[240:241]
	v_pk_mul_f32 v[78:79], v[78:79], v[242:243]
	v_cvt_pk_bf16_f32 v76, v76, v77
	v_cvt_pk_bf16_f32 v77, v78, v79
	global_store_dwordx2 v[130:131], v[76:77], off offset:96
	s_waitcnt vmcnt(31)
	v_pk_mul_f32 v[64:65], v[64:65], v[156:157]
	v_pk_mul_f32 v[66:67], v[66:67], v[158:159]
	v_lshlrev_b32_e32 v240, 16, v202
	v_and_b32_e32 v241, 0xffff0000, v202
	v_lshlrev_b32_e32 v242, 16, v203
	v_and_b32_e32 v243, 0xffff0000, v203
	v_pk_mul_f32 v[64:65], v[64:65], v[240:241]
	v_pk_mul_f32 v[66:67], v[66:67], v[242:243]
	v_cvt_pk_bf16_f32 v64, v64, v65
	v_cvt_pk_bf16_f32 v65, v66, v67
	global_store_dwordx2 v[134:135], v[64:65], off offset:96
	s_waitcnt vmcnt(31)
	v_pk_mul_f32 v[72:73], v[72:73], v[156:157]
	v_pk_mul_f32 v[74:75], v[74:75], v[158:159]
	v_lshlrev_b32_e32 v240, 16, v204
	v_and_b32_e32 v241, 0xffff0000, v204
	v_lshlrev_b32_e32 v242, 16, v205
	v_and_b32_e32 v243, 0xffff0000, v205
	v_pk_mul_f32 v[72:73], v[72:73], v[240:241]
	v_pk_mul_f32 v[74:75], v[74:75], v[242:243]
	v_cvt_pk_bf16_f32 v72, v72, v73
	v_cvt_pk_bf16_f32 v73, v74, v75
	global_store_dwordx2 v[136:137], v[72:73], off offset:96
	s_waitcnt vmcnt(31)
	v_pk_mul_f32 v[68:69], v[68:69], v[156:157]
	v_pk_mul_f32 v[70:71], v[70:71], v[158:159]
	v_lshlrev_b32_e32 v240, 16, v206
	v_and_b32_e32 v241, 0xffff0000, v206
	v_lshlrev_b32_e32 v242, 16, v207
	v_and_b32_e32 v243, 0xffff0000, v207
	v_pk_mul_f32 v[68:69], v[68:69], v[240:241]
	v_pk_mul_f32 v[70:71], v[70:71], v[242:243]
	v_cvt_pk_bf16_f32 v68, v68, v69
	v_cvt_pk_bf16_f32 v69, v70, v71
	global_store_dwordx2 v[138:139], v[68:69], off offset:96
	s_waitcnt vmcnt(31)
; __device__ __forceinline__ float bf_lo(u32 v) { return __uint_as_float(v << 16); }
; __device__ __forceinline__ float bf_hi(u32 v) { return __uint_as_float(v & 0xffff0000u); }
; __device__ __forceinline__ void gemm_tile(const TileDesc& td, char* shm_c, const int wv) {
;     ...
;     #pragma unroll
;     for (int ai = 0; ai < 2; ++ai)
;     #pragma unroll
;     for (int m = 0; m < 4; ++m) {
;       int f0 = td.brow + ai * 128 + m * 16 + ar_l;
;       float4 ps = *(const float4*)(td.aux + f0);
;       #pragma unroll
;       for (int bj = 0; bj < 2; ++bj)
;       #pragma unroll
;       for (int n = 0; n < 2; ++n) {
;         long o = (long)(td.bcol + bj * 128 + n * 16 + br_l) * td.ldo + f0;
;         uint2 g = *(const uint2*)(td.outb + o);
;         f32x4 v = acc[ai][bj][m][n];
;         uint2 pk;
;         pk.x = pack2(v[0] * ps.x * bf_lo(g.x), v[1] * ps.y * bf_hi(g.x));
;         pk.y = pack2(v[2] * ps.z * bf_lo(g.y), v[3] * ps.w * bf_hi(g.y));
;         *(uint2*)(td.outb + o) = pk;
;       }
;     }
	v_pk_mul_f32 v[60:61], v[60:61], v[160:161]
	v_pk_mul_f32 v[62:63], v[62:63], v[162:163]
	v_lshlrev_b32_e32 v240, 16, v208
	v_and_b32_e32 v241, 0xffff0000, v208
	v_lshlrev_b32_e32 v242, 16, v209
	v_and_b32_e32 v243, 0xffff0000, v209
	v_pk_mul_f32 v[60:61], v[60:61], v[240:241]
	v_pk_mul_f32 v[62:63], v[62:63], v[242:243]
	v_cvt_pk_bf16_f32 v60, v60, v61
	v_cvt_pk_bf16_f32 v61, v62, v63
	global_store_dwordx2 v[130:131], v[60:61], off offset:256
	s_waitcnt vmcnt(31)
	v_pk_mul_f32 v[48:49], v[48:49], v[160:161]
	v_pk_mul_f32 v[50:51], v[50:51], v[162:163]
	v_lshlrev_b32_e32 v240, 16, v210
	v_and_b32_e32 v241, 0xffff0000, v210
	v_lshlrev_b32_e32 v242, 16, v211
	v_and_b32_e32 v243, 0xffff0000, v211
	v_pk_mul_f32 v[48:49], v[48:49], v[240:241]
	v_pk_mul_f32 v[50:51], v[50:51], v[242:243]
	v_cvt_pk_bf16_f32 v48, v48, v49
	v_cvt_pk_bf16_f32 v49, v50, v51
	global_store_dwordx2 v[134:135], v[48:49], off offset:256
	s_waitcnt vmcnt(31)
	v_pk_mul_f32 v[56:57], v[56:57], v[160:161]
	v_pk_mul_f32 v[58:59], v[58:59], v[162:163]
	v_lshlrev_b32_e32 v240, 16, v212
	v_and_b32_e32 v241, 0xffff0000, v212
	v_lshlrev_b32_e32 v242, 16, v213
	v_and_b32_e32 v243, 0xffff0000, v213
	v_pk_mul_f32 v[56:57], v[56:57], v[240:241]
	v_pk_mul_f32 v[58:59], v[58:59], v[242:243]
	v_cvt_pk_bf16_f32 v56, v56, v57
	v_cvt_pk_bf16_f32 v57, v58, v59
	global_store_dwordx2 v[136:137], v[56:57], off offset:256
	s_waitcnt vmcnt(31)
	v_pk_mul_f32 v[52:53], v[52:53], v[160:161]
	v_pk_mul_f32 v[54:55], v[54:55], v[162:163]
	v_lshlrev_b32_e32 v240, 16, v214
	v_and_b32_e32 v241, 0xffff0000, v214
	v_lshlrev_b32_e32 v242, 16, v215
	v_and_b32_e32 v243, 0xffff0000, v215
	v_pk_mul_f32 v[52:53], v[52:53], v[240:241]
	v_pk_mul_f32 v[54:55], v[54:55], v[242:243]
	v_cvt_pk_bf16_f32 v52, v52, v53
	v_cvt_pk_bf16_f32 v53, v54, v55
	global_store_dwordx2 v[138:139], v[52:53], off offset:256
	s_waitcnt vmcnt(31)
	v_pk_mul_f32 v[44:45], v[44:45], v[164:165]
	v_pk_mul_f32 v[46:47], v[46:47], v[166:167]
	v_lshlrev_b32_e32 v240, 16, v216
	v_and_b32_e32 v241, 0xffff0000, v216
	v_lshlrev_b32_e32 v242, 16, v217
	v_and_b32_e32 v243, 0xffff0000, v217
	v_pk_mul_f32 v[44:45], v[44:45], v[240:241]
	v_pk_mul_f32 v[46:47], v[46:47], v[242:243]
	v_cvt_pk_bf16_f32 v44, v44, v45
	v_cvt_pk_bf16_f32 v45, v46, v47
	global_store_dwordx2 v[130:131], v[44:45], off offset:288
	s_waitcnt vmcnt(31)
	v_pk_mul_f32 v[32:33], v[32:33], v[164:165]
	v_pk_mul_f32 v[34:35], v[34:35], v[166:167]
	v_lshlrev_b32_e32 v240, 16, v218
	v_and_b32_e32 v241, 0xffff0000, v218
	v_lshlrev_b32_e32 v242, 16, v219
	v_and_b32_e32 v243, 0xffff0000, v219
	v_pk_mul_f32 v[32:33], v[32:33], v[240:241]
	v_pk_mul_f32 v[34:35], v[34:35], v[242:243]
	v_cvt_pk_bf16_f32 v32, v32, v33
	v_cvt_pk_bf16_f32 v33, v34, v35
	global_store_dwordx2 v[134:135], v[32:33], off offset:288
	s_waitcnt vmcnt(31)
	v_pk_mul_f32 v[40:41], v[40:41], v[164:165]
	v_pk_mul_f32 v[42:43], v[42:43], v[166:167]
	v_lshlrev_b32_e32 v240, 16, v220
	v_and_b32_e32 v241, 0xffff0000, v220
	v_lshlrev_b32_e32 v242, 16, v221
	v_and_b32_e32 v243, 0xffff0000, v221
	v_pk_mul_f32 v[40:41], v[40:41], v[240:241]
	v_pk_mul_f32 v[42:43], v[42:43], v[242:243]
	v_cvt_pk_bf16_f32 v40, v40, v41
	v_cvt_pk_bf16_f32 v41, v42, v43
	global_store_dwordx2 v[136:137], v[40:41], off offset:288
	s_waitcnt vmcnt(31)
	v_pk_mul_f32 v[36:37], v[36:37], v[164:165]
	v_pk_mul_f32 v[38:39], v[38:39], v[166:167]
	v_lshlrev_b32_e32 v240, 16, v222
	v_and_b32_e32 v241, 0xffff0000, v222
	v_lshlrev_b32_e32 v242, 16, v223
	v_and_b32_e32 v243, 0xffff0000, v223
	v_pk_mul_f32 v[36:37], v[36:37], v[240:241]
	v_pk_mul_f32 v[38:39], v[38:39], v[242:243]
	v_cvt_pk_bf16_f32 v36, v36, v37
	v_cvt_pk_bf16_f32 v37, v38, v39
	global_store_dwordx2 v[138:139], v[36:37], off offset:288
	s_waitcnt vmcnt(31)
; __device__ __forceinline__ float bf_lo(u32 v) { return __uint_as_float(v << 16); }
; __device__ __forceinline__ float bf_hi(u32 v) { return __uint_as_float(v & 0xffff0000u); }
; __device__ __forceinline__ void gemm_tile(const TileDesc& td, char* shm_c, const int wv) {
;     ...
;     #pragma unroll
;     for (int ai = 0; ai < 2; ++ai)
;     #pragma unroll
;     for (int m = 0; m < 4; ++m) {
;       int f0 = td.brow + ai * 128 + m * 16 + ar_l;
;       float4 ps = *(const float4*)(td.aux + f0);
;       #pragma unroll
;       for (int bj = 0; bj < 2; ++bj)
;       #pragma unroll
;       for (int n = 0; n < 2; ++n) {
;         long o = (long)(td.bcol + bj * 128 + n * 16 + br_l) * td.ldo + f0;
;         uint2 g = *(const uint2*)(td.outb + o);
;         f32x4 v = acc[ai][bj][m][n];
;         uint2 pk;
;         pk.x = pack2(v[0] * ps.x * bf_lo(g.x), v[1] * ps.y * bf_hi(g.x));
;         pk.y = pack2(v[2] * ps.z * bf_lo(g.y), v[3] * ps.w * bf_hi(g.y));
;         *(uint2*)(td.outb + o) = pk;
;       }
;     }
	v_pk_mul_f32 v[28:29], v[28:29], v[168:169]
	v_pk_mul_f32 v[30:31], v[30:31], v[170:171]
	v_lshlrev_b32_e32 v240, 16, v224
	v_and_b32_e32 v241, 0xffff0000, v224
	v_lshlrev_b32_e32 v242, 16, v225
	v_and_b32_e32 v243, 0xffff0000, v225
	v_pk_mul_f32 v[28:29], v[28:29], v[240:241]
	v_pk_mul_f32 v[30:31], v[30:31], v[242:243]
	v_cvt_pk_bf16_f32 v28, v28, v29
	v_cvt_pk_bf16_f32 v29, v30, v31
	global_store_dwordx2 v[130:131], v[28:29], off offset:320
	s_waitcnt vmcnt(31)
	v_pk_mul_f32 v[16:17], v[16:17], v[168:169]
	v_pk_mul_f32 v[18:19], v[18:19], v[170:171]
	v_lshlrev_b32_e32 v240, 16, v226
	v_and_b32_e32 v241, 0xffff0000, v226
	v_lshlrev_b32_e32 v242, 16, v227
	v_and_b32_e32 v243, 0xffff0000, v227
	v_pk_mul_f32 v[16:17], v[16:17], v[240:241]
	v_pk_mul_f32 v[18:19], v[18:19], v[242:243]
	v_cvt_pk_bf16_f32 v16, v16, v17
	v_cvt_pk_bf16_f32 v17, v18, v19
	global_store_dwordx2 v[134:135], v[16:17], off offset:320
	s_waitcnt vmcnt(31)
	v_pk_mul_f32 v[24:25], v[24:25], v[168:169]
	v_pk_mul_f32 v[26:27], v[26:27], v[170:171]
	v_lshlrev_b32_e32 v240, 16, v228
	v_and_b32_e32 v241, 0xffff0000, v228
	v_lshlrev_b32_e32 v242, 16, v229
	v_and_b32_e32 v243, 0xffff0000, v229
	v_pk_mul_f32 v[24:25], v[24:25], v[240:241]
	v_pk_mul_f32 v[26:27], v[26:27], v[242:243]
	v_cvt_pk_bf16_f32 v24, v24, v25
	v_cvt_pk_bf16_f32 v25, v26, v27
	global_store_dwordx2 v[136:137], v[24:25], off offset:320
	s_waitcnt vmcnt(31)
	v_pk_mul_f32 v[20:21], v[20:21], v[168:169]
	v_pk_mul_f32 v[22:23], v[22:23], v[170:171]
	v_lshlrev_b32_e32 v240, 16, v230
	v_and_b32_e32 v241, 0xffff0000, v230
	v_lshlrev_b32_e32 v242, 16, v231
	v_and_b32_e32 v243, 0xffff0000, v231
	v_pk_mul_f32 v[20:21], v[20:21], v[240:241]
	v_pk_mul_f32 v[22:23], v[22:23], v[242:243]
	v_cvt_pk_bf16_f32 v20, v20, v21
	v_cvt_pk_bf16_f32 v21, v22, v23
	global_store_dwordx2 v[138:139], v[20:21], off offset:320
	s_waitcnt vmcnt(31)
	v_pk_mul_f32 v[12:13], v[12:13], v[172:173]
	v_pk_mul_f32 v[14:15], v[14:15], v[174:175]
	v_lshlrev_b32_e32 v240, 16, v232
	v_and_b32_e32 v241, 0xffff0000, v232
	v_lshlrev_b32_e32 v242, 16, v233
	v_and_b32_e32 v243, 0xffff0000, v233
	v_pk_mul_f32 v[12:13], v[12:13], v[240:241]
	v_pk_mul_f32 v[14:15], v[14:15], v[242:243]
	v_cvt_pk_bf16_f32 v12, v12, v13
	v_cvt_pk_bf16_f32 v13, v14, v15
	global_store_dwordx2 v[130:131], v[12:13], off offset:352
	s_waitcnt vmcnt(31)
	v_pk_mul_f32 v[0:1], v[0:1], v[172:173]
	v_pk_mul_f32 v[2:3], v[2:3], v[174:175]
	v_lshlrev_b32_e32 v240, 16, v234
	v_and_b32_e32 v241, 0xffff0000, v234
	v_lshlrev_b32_e32 v242, 16, v235
	v_and_b32_e32 v243, 0xffff0000, v235
	v_pk_mul_f32 v[0:1], v[0:1], v[240:241]
	v_pk_mul_f32 v[2:3], v[2:3], v[242:243]
	v_cvt_pk_bf16_f32 v0, v0, v1
	v_cvt_pk_bf16_f32 v1, v2, v3
	global_store_dwordx2 v[134:135], v[0:1], off offset:352
	s_waitcnt vmcnt(31)
	v_pk_mul_f32 v[4:5], v[4:5], v[172:173]
	v_pk_mul_f32 v[6:7], v[6:7], v[174:175]
	v_lshlrev_b32_e32 v240, 16, v236
	v_and_b32_e32 v241, 0xffff0000, v236
	v_lshlrev_b32_e32 v242, 16, v237
	v_and_b32_e32 v243, 0xffff0000, v237
	v_pk_mul_f32 v[4:5], v[4:5], v[240:241]
	v_pk_mul_f32 v[6:7], v[6:7], v[242:243]
	v_cvt_pk_bf16_f32 v4, v4, v5
	v_cvt_pk_bf16_f32 v5, v6, v7
	global_store_dwordx2 v[136:137], v[4:5], off offset:352
	s_waitcnt vmcnt(31)
	v_pk_mul_f32 v[8:9], v[8:9], v[172:173]
	v_pk_mul_f32 v[10:11], v[10:11], v[174:175]
	v_lshlrev_b32_e32 v240, 16, v238
	v_and_b32_e32 v241, 0xffff0000, v238
	v_lshlrev_b32_e32 v242, 16, v239
	v_and_b32_e32 v243, 0xffff0000, v239
	v_pk_mul_f32 v[8:9], v[8:9], v[240:241]
	v_pk_mul_f32 v[10:11], v[10:11], v[242:243]
	v_cvt_pk_bf16_f32 v8, v8, v9
	v_cvt_pk_bf16_f32 v9, v10, v11
	global_store_dwordx2 v[138:139], v[8:9], off offset:352
	s_cbranch_scc0 .LBB0_489

; __device__ __forceinline__ void gemm_tile(const TileDesc& td, char* shm_c, const int wv) {
;     ...
;   } else if (mode == EPI_NORM) {
;     float* red = (float*)(shm_c + 131072);
;     const int e_wr = e_wid >> 2, e_fq = e_lane >> 4;
;     float ssq[2][2][2];
;     #pragma unroll
;     for (int ai = 0; ai < 2; ++ai)
;     #pragma unroll
;     for (int bj = 0; bj < 2; ++bj)
;     #pragma unroll
;     for (int n = 0; n < 2; ++n) {
;       float t = 0.f;
;       #pragma unroll
;       for (int m = 0; m < 4; ++m) { const f32x4 v = acc[ai][bj][m][n]; t += v[0] * v[0] + v[1] * v[1] + v[2] * v[2] + v[3] * v[3]; }
;       t += sx(t, 16, e_lane); t += sx(t, 32, e_lane);
;       ssq[ai][bj][n] = t;
;       if (e_fq == 0) red[(e_wr * 2 + ai) * 256 + bj * 128 + n * 16 + br_l] = t;
;     }
.LBB0_550:
	s_mov_b64 s[48:49], -1
	s_mov_b64 s[46:47], 0
	s_cmp_lt_i32 s84, 4
	s_mov_b64 s[4:5], 0
	s_cbranch_scc1 .LBB0_578
	s_cmp_gt_i32 s84, 4
	s_cbranch_scc0 .LBB0_575
	s_cmp_gt_i32 s84, 6
	s_mov_b64 s[4:5], -1
	s_cbranch_scc0 .LBB0_570
	v_mul_f32_e32 v131, v125, v125
	v_mul_f32_e32 v132, v117, v117
	v_fmac_f32_e32 v131, v124, v124
	v_fmac_f32_e32 v132, v116, v116
	v_fmac_f32_e32 v131, v126, v126
	v_fmac_f32_e32 v132, v118, v118
	v_fmac_f32_e32 v131, v127, v127
	v_fmac_f32_e32 v132, v119, v119
	v_add_f32_e32 v131, v131, v132
	v_mul_f32_e32 v132, v109, v109
	v_fmac_f32_e32 v132, v108, v108
	v_fmac_f32_e32 v132, v110, v110
	v_fmac_f32_e32 v132, v111, v111
	v_add_f32_e32 v131, v131, v132
	v_mul_f32_e32 v132, v101, v101
	v_fmac_f32_e32 v132, v100, v100
	v_and_b32_e32 v129, 63, v128
	v_fmac_f32_e32 v132, v102, v102
	v_lshlrev_b32_e32 v130, 2, v129
	v_fmac_f32_e32 v132, v103, v103
	v_xor_b32_e32 v128, 64, v130
	v_add_f32_e32 v132, v131, v132
	ds_bpermute_b32 v137, v128, v132
	v_xor_b32_e32 v131, 0x80, v130
	v_cmp_gt_u32_e32 vcc, 16, v129
	v_lshl_add_u32 v130, v164, 2, s63
	s_waitcnt lgkmcnt(0)
	v_add_f32_e32 v132, v132, v137
	ds_bpermute_b32 v137, v131, v132
	s_waitcnt lgkmcnt(0)
	v_add_f32_e32 v129, v132, v137
	s_and_saveexec_b64 s[4:5], vcc
	ds_write_b32 v130, v129
	s_or_b64 exec, exec, s[4:5]
	v_mul_f32_e32 v132, v121, v121
	v_mul_f32_e32 v137, v113, v113
	v_fmac_f32_e32 v132, v120, v120
	v_fmac_f32_e32 v137, v112, v112
	v_fmac_f32_e32 v132, v122, v122
	v_fmac_f32_e32 v137, v114, v114
	v_fmac_f32_e32 v132, v123, v123
	v_fmac_f32_e32 v137, v115, v115
	v_add_f32_e32 v132, v132, v137
	v_mul_f32_e32 v137, v105, v105
	v_fmac_f32_e32 v137, v104, v104
	v_fmac_f32_e32 v137, v106, v106
	v_fmac_f32_e32 v137, v107, v107
	v_add_f32_e32 v132, v132, v137
	v_mul_f32_e32 v137, v97, v97
	v_fmac_f32_e32 v137, v96, v96
	v_fmac_f32_e32 v137, v98, v98
	v_fmac_f32_e32 v137, v99, v99
	v_add_f32_e32 v132, v132, v137
	ds_bpermute_b32 v137, v128, v132
	s_waitcnt lgkmcnt(0)
	v_add_f32_e32 v132, v132, v137
	ds_bpermute_b32 v137, v131, v132
	s_waitcnt lgkmcnt(0)
	v_add_f32_e32 v142, v132, v137
	s_and_saveexec_b64 s[4:5], vcc
	ds_write_b32 v130, v142 offset:64
	s_or_b64 exec, exec, s[4:5]
	v_mul_f32_e32 v132, v93, v93
	v_mul_f32_e32 v137, v85, v85
	v_fmac_f32_e32 v132, v92, v92
	v_fmac_f32_e32 v137, v84, v84
	v_fmac_f32_e32 v132, v94, v94
	v_fmac_f32_e32 v137, v86, v86
	v_fmac_f32_e32 v132, v95, v95
	v_fmac_f32_e32 v137, v87, v87
	v_add_f32_e32 v132, v132, v137
	v_mul_f32_e32 v137, v77, v77
	v_fmac_f32_e32 v137, v76, v76
	v_fmac_f32_e32 v137, v78, v78
	v_fmac_f32_e32 v137, v79, v79
	v_add_f32_e32 v132, v132, v137
	v_mul_f32_e32 v137, v69, v69
	v_fmac_f32_e32 v137, v68, v68
	v_fmac_f32_e32 v137, v70, v70
	v_fmac_f32_e32 v137, v71, v71
	v_add_f32_e32 v132, v132, v137
	ds_bpermute_b32 v137, v128, v132
	s_waitcnt lgkmcnt(0)
	v_add_f32_e32 v132, v132, v137
	ds_bpermute_b32 v137, v131, v132
	s_waitcnt lgkmcnt(0)
	v_add_f32_e32 v140, v132, v137
	s_and_saveexec_b64 s[4:5], vcc
	ds_write_b32 v130, v140 offset:512
	s_or_b64 exec, exec, s[4:5]
	v_mul_f32_e32 v132, v89, v89
	v_mul_f32_e32 v137, v81, v81
	v_fmac_f32_e32 v132, v88, v88
	v_fmac_f32_e32 v137, v80, v80
	v_fmac_f32_e32 v132, v90, v90
	v_fmac_f32_e32 v137, v82, v82
	v_fmac_f32_e32 v132, v91, v91
	v_fmac_f32_e32 v137, v83, v83
	v_add_f32_e32 v132, v132, v137
	v_mul_f32_e32 v137, v73, v73
	v_fmac_f32_e32 v137, v72, v72
	v_fmac_f32_e32 v137, v74, v74
	v_fmac_f32_e32 v137, v75, v75
	v_add_f32_e32 v132, v132, v137
	v_mul_f32_e32 v137, v65, v65
	v_fmac_f32_e32 v137, v64, v64
	v_fmac_f32_e32 v137, v66, v66
	v_fmac_f32_e32 v137, v67, v67
	v_add_f32_e32 v132, v132, v137
	ds_bpermute_b32 v137, v128, v132
	s_waitcnt lgkmcnt(0)
	v_add_f32_e32 v132, v132, v137
	ds_bpermute_b32 v137, v131, v132
	s_waitcnt lgkmcnt(0)
	v_add_f32_e32 v157, v132, v137
	s_and_saveexec_b64 s[4:5], vcc
	ds_write_b32 v130, v157 offset:576
	s_or_b64 exec, exec, s[4:5]
	v_mul_f32_e32 v132, v61, v61
	v_mul_f32_e32 v137, v53, v53
	v_fmac_f32_e32 v132, v60, v60
	v_fmac_f32_e32 v137, v52, v52
	v_fmac_f32_e32 v132, v62, v62
	v_fmac_f32_e32 v137, v54, v54
	v_fmac_f32_e32 v132, v63, v63
	v_fmac_f32_e32 v137, v55, v55
	v_add_f32_e32 v132, v132, v137
	v_mul_f32_e32 v137, v45, v45
	v_fmac_f32_e32 v137, v44, v44
	v_fmac_f32_e32 v137, v46, v46
	v_fmac_f32_e32 v137, v47, v47
	v_add_f32_e32 v132, v132, v137
	v_mul_f32_e32 v137, v37, v37
	v_fmac_f32_e32 v137, v36, v36
	v_fmac_f32_e32 v137, v38, v38
	v_fmac_f32_e32 v137, v39, v39
	v_add_f32_e32 v132, v132, v137
	ds_bpermute_b32 v137, v128, v132
	s_waitcnt lgkmcnt(0)
	v_add_f32_e32 v132, v132, v137
	ds_bpermute_b32 v137, v131, v132
	s_waitcnt lgkmcnt(0)
	v_add_f32_e32 v155, v132, v137
	s_and_saveexec_b64 s[4:5], vcc
	ds_write_b32 v130, v155 offset:1024
	s_or_b64 exec, exec, s[4:5]
	v_mul_f32_e32 v132, v57, v57
	v_mul_f32_e32 v137, v49, v49
	v_fmac_f32_e32 v132, v56, v56
	v_fmac_f32_e32 v137, v48, v48
	v_fmac_f32_e32 v132, v58, v58
	v_fmac_f32_e32 v137, v50, v50
	v_fmac_f32_e32 v132, v59, v59
	v_fmac_f32_e32 v137, v51, v51
	v_add_f32_e32 v132, v132, v137
	v_mul_f32_e32 v137, v41, v41
	v_fmac_f32_e32 v137, v40, v40
	v_fmac_f32_e32 v137, v42, v42
	v_fmac_f32_e32 v137, v43, v43
	v_add_f32_e32 v132, v132, v137
	v_mul_f32_e32 v137, v33, v33
	v_fmac_f32_e32 v137, v32, v32
	v_fmac_f32_e32 v137, v34, v34
	v_fmac_f32_e32 v137, v35, v35
	v_add_f32_e32 v132, v132, v137
	ds_bpermute_b32 v137, v128, v132
	s_waitcnt lgkmcnt(0)
	v_add_f32_e32 v132, v132, v137
	ds_bpermute_b32 v137, v131, v132
	s_waitcnt lgkmcnt(0)
; __device__ __forceinline__ void gemm_tile(const TileDesc& td, char* shm_c, const int wv) {
;     ...
;     __syncthreads();
;     #pragma unroll
;     for (int ai = 0; ai < 2; ++ai)
;     #pragma unroll
;     for (int bj = 0; bj < 2; ++bj)
;     #pragma unroll
;     for (int n = 0; n < 2; ++n) {
;       const float tot = ssq[ai][bj][n] + red[((1 - e_wr) * 2 + ai) * 256 + bj * 128 + n * 16 + br_l];
;       const float rstd = 1.0f / sqrtf(tot * (1.0f / 128.f) + EPS);
;       #pragma unroll
;       for (int m = 0; m < 4; ++m) {
;         const float4 g = *(const float4*)(td.aux + m * 16 + ar_l);
;         f32x4 v = acc[ai][bj][m][n];
;         long o = (long)(td.bcol + bj * 128 + n * 16 + br_l) * td.ldo + (td.brow + ai * 128 + m * 16 + ar_l);
;         uint2 pk; pk.x = pack2(v[0] * rstd * g.x, v[1] * rstd * g.y); pk.y = pack2(v[2] * rstd * g.z, v[3] * rstd * g.w);
;         *(uint2*)(td.outb + o) = pk;
;       }
	v_add_f32_e32 v154, v132, v137
	s_and_saveexec_b64 s[4:5], vcc
	ds_write_b32 v130, v154 offset:1088
	s_or_b64 exec, exec, s[4:5]
	v_mul_f32_e32 v132, v29, v29
	v_mul_f32_e32 v137, v21, v21
	v_fmac_f32_e32 v132, v28, v28
	v_fmac_f32_e32 v137, v20, v20
	v_fmac_f32_e32 v132, v30, v30
	v_fmac_f32_e32 v137, v22, v22
	v_fmac_f32_e32 v132, v31, v31
	v_fmac_f32_e32 v137, v23, v23
	v_add_f32_e32 v132, v132, v137
	v_mul_f32_e32 v137, v13, v13
	v_fmac_f32_e32 v137, v12, v12
	v_fmac_f32_e32 v137, v14, v14
	v_fmac_f32_e32 v137, v15, v15
	v_add_f32_e32 v132, v132, v137
	v_mul_f32_e32 v137, v5, v5
	v_fmac_f32_e32 v137, v4, v4
	v_fmac_f32_e32 v137, v6, v6
	v_fmac_f32_e32 v137, v7, v7
	v_add_f32_e32 v132, v132, v137
	ds_bpermute_b32 v137, v128, v132
	s_waitcnt lgkmcnt(0)
	v_add_f32_e32 v132, v132, v137
	ds_bpermute_b32 v137, v131, v132
	s_waitcnt lgkmcnt(0)
	v_add_f32_e32 v153, v132, v137
	s_and_saveexec_b64 s[4:5], vcc
	ds_write_b32 v130, v153 offset:1536
	s_or_b64 exec, exec, s[4:5]
	v_mul_f32_e32 v132, v25, v25
	v_mul_f32_e32 v137, v17, v17
	v_fmac_f32_e32 v132, v24, v24
	v_fmac_f32_e32 v137, v16, v16
	v_fmac_f32_e32 v132, v26, v26
	v_fmac_f32_e32 v137, v18, v18
	v_fmac_f32_e32 v132, v27, v27
	v_fmac_f32_e32 v137, v19, v19
	v_add_f32_e32 v132, v132, v137
	v_mul_f32_e32 v137, v9, v9
	v_fmac_f32_e32 v137, v8, v8
	v_fmac_f32_e32 v137, v10, v10
	v_fmac_f32_e32 v137, v11, v11
	v_add_f32_e32 v132, v132, v137
	v_mul_f32_e32 v137, v1, v1
	v_fmac_f32_e32 v137, v0, v0
	v_fmac_f32_e32 v137, v2, v2
	v_fmac_f32_e32 v137, v3, v3
	v_add_f32_e32 v132, v132, v137
	ds_bpermute_b32 v128, v128, v132
	s_waitcnt lgkmcnt(0)
	v_add_f32_e32 v128, v132, v128
	ds_bpermute_b32 v131, v131, v128
	s_waitcnt lgkmcnt(0)
	v_add_f32_e32 v152, v128, v131
	s_and_saveexec_b64 s[4:5], vcc
	ds_write_b32 v130, v152 offset:1600
	s_or_b64 exec, exec, s[4:5]
	v_lshlrev_b32_e32 v156, 2, v164
	v_add_u32_e32 v128, s64, v156
	v_add_u32_e32 v141, 0x800, v128
	s_waitcnt vmcnt(0) lgkmcnt(0)
	s_barrier
	ds_read2_b32 v[138:139], v141 offset1:16
	v_or_b32_e32 v158, s50, v164
	s_waitcnt lgkmcnt(0)
	v_add_f32_e32 v128, v129, v138
	v_fmamk_f32 v128, v128, 0x3c000000, v160
	v_cmp_gt_f32_e32 vcc, s81, v128
	v_mul_f32_e32 v129, 0x4f800000, v128
	s_nop 0
	v_cndmask_b32_e32 v128, v128, v129, vcc
	v_sqrt_f32_e32 v129, v128
	s_nop 0
	v_add_u32_e32 v130, -1, v129
	v_fma_f32 v131, -v130, v129, v128
	v_cmp_ge_f32_e64 s[4:5], 0, v131
	v_add_u32_e32 v131, 1, v129
	s_nop 0
	v_cndmask_b32_e64 v130, v129, v130, s[4:5]
	v_fma_f32 v129, -v131, v129, v128
	v_cmp_lt_f32_e64 s[4:5], 0, v129
	s_nop 1
	v_cndmask_b32_e64 v129, v130, v131, s[4:5]
	v_mul_f32_e32 v130, 0x37800000, v129
	v_cndmask_b32_e32 v129, v129, v130, vcc
	v_cmp_class_f32_e32 vcc, v128, v161
	s_nop 1
	v_cndmask_b32_e32 v128, v129, v128, vcc
	v_div_scale_f32 v129, s[2:3], v128, v128, 1.0
	v_rcp_f32_e32 v130, v129
	s_ashr_i32 s2, s50, 31
	s_mul_i32 s2, s34, s2
	v_fma_f32 v131, -v129, v130, 1.0
	v_fmac_f32_e32 v130, v131, v130
	v_div_scale_f32 v131, vcc, 1.0, v128, 1.0
	v_mul_f32_e32 v132, v131, v130
	v_fma_f32 v137, -v129, v132, v131
	v_fmac_f32_e32 v132, v137, v130
	v_lshlrev_b32_e32 v137, 2, v136
	global_load_dwordx4 v[236:239], v137, s[40:41]
	global_load_dwordx4 v[240:243], v137, s[40:41] offset:64
	global_load_dwordx4 v[244:247], v137, s[40:41] offset:128
	global_load_dwordx4 v[248:251], v137, s[40:41] offset:192
	v_fma_f32 v129, -v129, v132, v131
	v_div_fmas_f32 v129, v129, v130, v132
	v_div_fixup_f32 v132, v129, v128, 1.0
	v_pk_mul_f32 v[148:149], v[124:125], v[132:133] op_sel_hi:[1,0]
	v_mul_lo_u32 v130, s35, v158
	v_mad_u64_u32 v[128:129], s[4:5], s34, v158, 0
	v_add3_u32 v129, v129, s2, v130
	v_add_u32_e32 v130, s14, v136
	v_ashrrev_i32_e32 v131, 31, v130
	v_lshl_add_u64 v[128:129], v[128:129], 1, s[36:37]
	v_pk_mul_f32 v[166:167], v[116:117], v[132:133] op_sel_hi:[1,0]
	v_add_u32_e32 v150, 16, v130
	v_ashrrev_i32_e32 v151, 31, v150
	v_pk_mul_f32 v[168:169], v[108:109], v[132:133] op_sel_hi:[1,0]
	v_pk_mul_f32 v[170:171], v[100:101], v[132:133] op_sel_hi:[1,0]
	s_waitcnt vmcnt(0)
	v_pk_mul_f32 v[144:145], v[236:237], v[148:149]
	s_nop 0
	v_cvt_pk_bf16_f32 v148, v144, v145
	v_pk_mul_f32 v[144:145], v[126:127], v[132:133] op_sel_hi:[1,0]
	s_nop 0
	v_pk_mul_f32 v[144:145], v[238:239], v[144:145]
	s_nop 0
	v_cvt_pk_bf16_f32 v149, v144, v145
	v_lshlrev_b64 v[144:145], 1, v[130:131]
	v_lshl_add_u64 v[146:147], v[128:129], 0, v[144:145]
	global_store_dwordx2 v[146:147], v[148:149], off
	v_add_f32_e32 v131, v142, v139
	v_fmamk_f32 v131, v131, 0x3c000000, v160
	v_cmp_gt_f32_e32 vcc, s81, v131
	v_pk_mul_f32 v[146:147], v[166:167], v[240:241]
	s_nop 0
	v_cvt_pk_bf16_f32 v166, v146, v147
	v_pk_mul_f32 v[146:147], v[118:119], v[132:133] op_sel_hi:[1,0]
	s_nop 0
	v_pk_mul_f32 v[146:147], v[146:147], v[242:243]
	s_nop 0
	v_cvt_pk_bf16_f32 v167, v146, v147
	v_lshlrev_b64 v[146:147], 1, v[150:151]
	v_lshl_add_u64 v[148:149], v[128:129], 0, v[146:147]
	global_store_dwordx2 v[148:149], v[166:167], off
	v_add_u32_e32 v166, 32, v130
	v_ashrrev_i32_e32 v167, 31, v166
	v_pk_mul_f32 v[148:149], v[168:169], v[244:245]
	s_nop 0
	v_cvt_pk_bf16_f32 v168, v148, v149
	v_pk_mul_f32 v[148:149], v[110:111], v[132:133] op_sel_hi:[1,0]
	s_nop 0
	v_pk_mul_f32 v[148:149], v[148:149], v[246:247]
	s_nop 0
	v_cvt_pk_bf16_f32 v169, v148, v149
	v_lshlrev_b64 v[148:149], 1, v[166:167]
	v_lshl_add_u64 v[150:151], v[128:129], 0, v[148:149]
	global_store_dwordx2 v[150:151], v[168:169], off
	v_add_u32_e32 v150, 48, v130
	v_ashrrev_i32_e32 v151, 31, v150
	v_lshlrev_b64 v[150:151], 1, v[150:151]
	v_pk_mul_f32 v[166:167], v[170:171], v[248:249]
	v_pk_mul_f32 v[170:171], v[102:103], v[132:133] op_sel_hi:[1,0]
; __device__ __forceinline__ void gemm_tile(const TileDesc& td, char* shm_c, const int wv) {
;     ...
;     #pragma unroll
;     for (int ai = 0; ai < 2; ++ai)
;     #pragma unroll
;     for (int bj = 0; bj < 2; ++bj)
;     #pragma unroll
;     for (int n = 0; n < 2; ++n) {
;       const float tot = ssq[ai][bj][n] + red[((1 - e_wr) * 2 + ai) * 256 + bj * 128 + n * 16 + br_l];
;       const float rstd = 1.0f / sqrtf(tot * (1.0f / 128.f) + EPS);
;       #pragma unroll
;       for (int m = 0; m < 4; ++m) {
;         const float4 g = *(const float4*)(td.aux + m * 16 + ar_l);
;         f32x4 v = acc[ai][bj][m][n];
;         long o = (long)(td.bcol + bj * 128 + n * 16 + br_l) * td.ldo + (td.brow + ai * 128 + m * 16 + ar_l);
;         uint2 pk; pk.x = pack2(v[0] * rstd * g.x, v[1] * rstd * g.y); pk.y = pack2(v[2] * rstd * g.z, v[3] * rstd * g.w);
;         *(uint2*)(td.outb + o) = pk;
;       }
	v_cvt_pk_bf16_f32 v166, v166, v167
	v_pk_mul_f32 v[168:169], v[170:171], v[250:251]
	v_mul_f32_e32 v132, 0x4f800000, v131
	v_cvt_pk_bf16_f32 v167, v168, v169
	v_lshl_add_u64 v[168:169], v[128:129], 0, v[150:151]
	global_store_dwordx2 v[168:169], v[166:167], off
	v_cndmask_b32_e32 v131, v131, v132, vcc
	v_sqrt_f32_e32 v132, v131
	s_nop 0
	v_add_u32_e32 v138, -1, v132
	v_fma_f32 v139, -v138, v132, v131
	v_cmp_ge_f32_e64 s[4:5], 0, v139
	v_add_u32_e32 v139, 1, v132
	s_nop 0
	v_cndmask_b32_e64 v138, v132, v138, s[4:5]
	v_fma_f32 v132, -v139, v132, v131
	v_cmp_lt_f32_e64 s[4:5], 0, v132
	s_nop 1
	v_cndmask_b32_e64 v132, v138, v139, s[4:5]
	v_mul_f32_e32 v138, 0x37800000, v132
	v_cndmask_b32_e32 v132, v132, v138, vcc
	v_cmp_class_f32_e32 vcc, v131, v161
	s_nop 1
	v_cndmask_b32_e32 v131, v132, v131, vcc
	v_div_scale_f32 v132, s[4:5], v131, v131, 1.0
	v_rcp_f32_e32 v138, v132
	s_nop 0
	v_fma_f32 v139, -v132, v138, 1.0
	v_fmac_f32_e32 v138, v139, v138
	v_div_scale_f32 v139, vcc, 1.0, v131, 1.0
	v_mul_f32_e32 v142, v139, v138
	v_fma_f32 v143, -v132, v142, v139
	v_fmac_f32_e32 v142, v143, v138
	v_fma_f32 v132, -v132, v142, v139
	v_div_fmas_f32 v132, v132, v138, v142
	v_div_fixup_f32 v132, v132, v131, 1.0
	v_or_b32_e32 v131, 16, v158
	v_mul_lo_u32 v142, s35, v131
	v_mad_u64_u32 v[138:139], s[4:5], s34, v131, 0
	v_add3_u32 v139, v139, s2, v142
	v_pk_mul_f32 v[142:143], v[120:121], v[132:133] op_sel_hi:[1,0]
	v_lshl_add_u64 v[138:139], v[138:139], 1, s[36:37]
	v_pk_mul_f32 v[142:143], v[236:237], v[142:143]
	v_pk_mul_f32 v[166:167], v[122:123], v[132:133] op_sel_hi:[1,0]
	v_cvt_pk_bf16_f32 v142, v142, v143
	v_pk_mul_f32 v[166:167], v[238:239], v[166:167]
	s_nop 0
	v_cvt_pk_bf16_f32 v143, v166, v167
	v_lshl_add_u64 v[166:167], v[138:139], 0, v[144:145]
	global_store_dwordx2 v[166:167], v[142:143], off
	v_pk_mul_f32 v[142:143], v[112:113], v[132:133] op_sel_hi:[1,0]
	v_pk_mul_f32 v[142:143], v[142:143], v[240:241]
	v_pk_mul_f32 v[166:167], v[114:115], v[132:133] op_sel_hi:[1,0]
	v_cvt_pk_bf16_f32 v142, v142, v143
	v_pk_mul_f32 v[166:167], v[166:167], v[242:243]
	s_nop 0
	v_cvt_pk_bf16_f32 v143, v166, v167
	v_lshl_add_u64 v[166:167], v[138:139], 0, v[146:147]
	global_store_dwordx2 v[166:167], v[142:143], off
	v_pk_mul_f32 v[142:143], v[104:105], v[132:133] op_sel_hi:[1,0]
	v_pk_mul_f32 v[142:143], v[142:143], v[244:245]
	v_pk_mul_f32 v[166:167], v[106:107], v[132:133] op_sel_hi:[1,0]
	v_cvt_pk_bf16_f32 v142, v142, v143
	v_pk_mul_f32 v[166:167], v[166:167], v[246:247]
	s_nop 0
	v_cvt_pk_bf16_f32 v143, v166, v167
	v_lshl_add_u64 v[166:167], v[138:139], 0, v[148:149]
	global_store_dwordx2 v[166:167], v[142:143], off
	v_pk_mul_f32 v[142:143], v[96:97], v[132:133] op_sel_hi:[1,0]
	v_pk_mul_f32 v[142:143], v[142:143], v[248:249]
	v_pk_mul_f32 v[166:167], v[98:99], v[132:133] op_sel_hi:[1,0]
	v_cvt_pk_bf16_f32 v142, v142, v143
	v_pk_mul_f32 v[166:167], v[166:167], v[250:251]
	s_nop 0
	v_cvt_pk_bf16_f32 v143, v166, v167
	v_lshl_add_u64 v[166:167], v[138:139], 0, v[150:151]
	global_store_dwordx2 v[166:167], v[142:143], off
	ds_read2_b32 v[142:143], v141 offset0:128 offset1:144
	s_waitcnt lgkmcnt(0)
	v_add_f32_e32 v131, v140, v142
	v_fmamk_f32 v131, v131, 0x3c000000, v160
	v_cmp_gt_f32_e32 vcc, s81, v131
	v_mul_f32_e32 v132, 0x4f800000, v131
	s_nop 0
	v_cndmask_b32_e32 v131, v131, v132, vcc
	v_sqrt_f32_e32 v132, v131
	s_nop 0
	v_add_u32_e32 v140, -1, v132
	v_fma_f32 v141, -v140, v132, v131
	v_cmp_ge_f32_e64 s[4:5], 0, v141
	v_add_u32_e32 v141, 1, v132
	s_nop 0
	v_cndmask_b32_e64 v140, v132, v140, s[4:5]
	v_fma_f32 v132, -v141, v132, v131
	v_cmp_lt_f32_e64 s[4:5], 0, v132
	s_nop 1
	v_cndmask_b32_e64 v132, v140, v141, s[4:5]
	v_mul_f32_e32 v140, 0x37800000, v132
	v_cndmask_b32_e32 v132, v132, v140, vcc
	v_cmp_class_f32_e32 vcc, v131, v161
	s_nop 1
	v_cndmask_b32_e32 v131, v132, v131, vcc
	v_div_scale_f32 v132, s[4:5], v131, v131, 1.0
	v_rcp_f32_e32 v140, v132
	s_nop 0
	v_fma_f32 v141, -v132, v140, 1.0
	v_fmac_f32_e32 v140, v141, v140
	v_div_scale_f32 v141, vcc, 1.0, v131, 1.0
	v_mul_f32_e32 v142, v141, v140
	v_fma_f32 v159, -v132, v142, v141
	v_fmac_f32_e32 v142, v159, v140
	v_fma_f32 v132, -v132, v142, v141
	v_div_fmas_f32 v132, v132, v140, v142
	v_div_fixup_f32 v132, v132, v131, 1.0
	v_or_b32_e32 v131, 0x80, v158
	v_mul_lo_u32 v142, s35, v131
	v_mad_u64_u32 v[140:141], s[4:5], s34, v131, 0
	v_pk_mul_f32 v[170:171], v[92:93], v[132:133] op_sel_hi:[1,0]
	v_add3_u32 v141, v141, s2, v142
	v_lshl_add_u64 v[140:141], v[140:141], 1, s[36:37]
	v_add_f32_e32 v131, v157, v143
	v_fmamk_f32 v131, v131, 0x3c000000, v160
	v_cmp_gt_f32_e32 vcc, s81, v131
	v_pk_mul_f32 v[166:167], v[236:237], v[170:171]
	v_pk_mul_f32 v[170:171], v[94:95], v[132:133] op_sel_hi:[1,0]
	v_cvt_pk_bf16_f32 v166, v166, v167
	v_pk_mul_f32 v[168:169], v[238:239], v[170:171]
	v_pk_mul_f32 v[170:171], v[84:85], v[132:133] op_sel_hi:[1,0]
	v_cvt_pk_bf16_f32 v167, v168, v169
	v_lshl_add_u64 v[168:169], v[140:141], 0, v[144:145]
	global_store_dwordx2 v[168:169], v[166:167], off
	v_pk_mul_f32 v[166:167], v[170:171], v[240:241]
	v_pk_mul_f32 v[170:171], v[86:87], v[132:133] op_sel_hi:[1,0]
	v_cvt_pk_bf16_f32 v166, v166, v167
	v_pk_mul_f32 v[168:169], v[170:171], v[242:243]
	v_pk_mul_f32 v[170:171], v[76:77], v[132:133] op_sel_hi:[1,0]
	v_cvt_pk_bf16_f32 v167, v168, v169
	v_lshl_add_u64 v[168:169], v[140:141], 0, v[146:147]
	global_store_dwordx2 v[168:169], v[166:167], off
	v_pk_mul_f32 v[166:167], v[170:171], v[244:245]
	v_pk_mul_f32 v[170:171], v[78:79], v[132:133] op_sel_hi:[1,0]
	v_cvt_pk_bf16_f32 v166, v166, v167
	v_pk_mul_f32 v[168:169], v[170:171], v[246:247]
	v_pk_mul_f32 v[170:171], v[68:69], v[132:133] op_sel_hi:[1,0]
; __device__ __forceinline__ void gemm_tile(const TileDesc& td, char* shm_c, const int wv) {
;     ...
;     #pragma unroll
;     for (int ai = 0; ai < 2; ++ai)
;     #pragma unroll
;     for (int bj = 0; bj < 2; ++bj)
;     #pragma unroll
;     for (int n = 0; n < 2; ++n) {
;       const float tot = ssq[ai][bj][n] + red[((1 - e_wr) * 2 + ai) * 256 + bj * 128 + n * 16 + br_l];
;       const float rstd = 1.0f / sqrtf(tot * (1.0f / 128.f) + EPS);
;       #pragma unroll
;       for (int m = 0; m < 4; ++m) {
;         const float4 g = *(const float4*)(td.aux + m * 16 + ar_l);
;         f32x4 v = acc[ai][bj][m][n];
;         long o = (long)(td.bcol + bj * 128 + n * 16 + br_l) * td.ldo + (td.brow + ai * 128 + m * 16 + ar_l);
;         uint2 pk; pk.x = pack2(v[0] * rstd * g.x, v[1] * rstd * g.y); pk.y = pack2(v[2] * rstd * g.z, v[3] * rstd * g.w);
;         *(uint2*)(td.outb + o) = pk;
;       }
	v_cvt_pk_bf16_f32 v167, v168, v169
	v_lshl_add_u64 v[168:169], v[140:141], 0, v[148:149]
	global_store_dwordx2 v[168:169], v[166:167], off
	v_pk_mul_f32 v[166:167], v[170:171], v[248:249]
	v_pk_mul_f32 v[170:171], v[70:71], v[132:133] op_sel_hi:[1,0]
	v_cvt_pk_bf16_f32 v166, v166, v167
	v_pk_mul_f32 v[168:169], v[170:171], v[250:251]
	v_mul_f32_e32 v132, 0x4f800000, v131
	v_cvt_pk_bf16_f32 v167, v168, v169
	v_lshl_add_u64 v[168:169], v[140:141], 0, v[150:151]
	global_store_dwordx2 v[168:169], v[166:167], off
	v_cndmask_b32_e32 v131, v131, v132, vcc
	v_sqrt_f32_e32 v132, v131
	s_nop 0
	v_add_u32_e32 v142, -1, v132
	v_fma_f32 v143, -v142, v132, v131
	v_cmp_ge_f32_e64 s[4:5], 0, v143
	v_add_u32_e32 v143, 1, v132
	s_nop 0
	v_cndmask_b32_e64 v142, v132, v142, s[4:5]
	v_fma_f32 v132, -v143, v132, v131
	v_cmp_lt_f32_e64 s[4:5], 0, v132
	s_nop 1
	v_cndmask_b32_e64 v132, v142, v143, s[4:5]
	v_mul_f32_e32 v142, 0x37800000, v132
	v_cndmask_b32_e32 v132, v132, v142, vcc
	v_cmp_class_f32_e32 vcc, v131, v161
	s_nop 1
	v_cndmask_b32_e32 v131, v132, v131, vcc
	v_div_scale_f32 v132, s[4:5], v131, v131, 1.0
	v_rcp_f32_e32 v142, v132
	s_nop 0
	v_fma_f32 v143, -v132, v142, 1.0
	v_fmac_f32_e32 v142, v143, v142
	v_div_scale_f32 v143, vcc, 1.0, v131, 1.0
	v_mul_f32_e32 v157, v143, v142
	v_fma_f32 v159, -v132, v157, v143
	v_fmac_f32_e32 v157, v159, v142
	v_fma_f32 v132, -v132, v157, v143
	v_div_fmas_f32 v132, v132, v142, v157
	v_div_fixup_f32 v132, v132, v131, 1.0
	v_or_b32_e32 v131, 0x90, v158
	v_mul_lo_u32 v157, s35, v131
	v_mad_u64_u32 v[142:143], s[4:5], s34, v131, 0
	v_pk_mul_f32 v[158:159], v[88:89], v[132:133] op_sel_hi:[1,0]
	v_add3_u32 v143, v143, s2, v157
	v_lshl_add_u64 v[142:143], v[142:143], 1, s[36:37]
	v_lshl_add_u64 v[144:145], v[142:143], 0, v[144:145]
	v_lshl_add_u64 v[146:147], v[142:143], 0, v[146:147]
	v_add_u32_e32 v131, s65, v156
	v_add_u32_e32 v156, 0x800, v131
	v_pk_mul_f32 v[158:159], v[236:237], v[158:159]
	v_pk_mul_f32 v[166:167], v[90:91], v[132:133] op_sel_hi:[1,0]
	v_cvt_pk_bf16_f32 v158, v158, v159
	v_pk_mul_f32 v[166:167], v[238:239], v[166:167]
	s_nop 0
	v_cvt_pk_bf16_f32 v159, v166, v167
	global_store_dwordx2 v[144:145], v[158:159], off
	v_pk_mul_f32 v[144:145], v[80:81], v[132:133] op_sel_hi:[1,0]
	v_pk_mul_f32 v[158:159], v[82:83], v[132:133] op_sel_hi:[1,0]
	v_pk_mul_f32 v[144:145], v[144:145], v[240:241]
	v_pk_mul_f32 v[158:159], v[158:159], v[242:243]
	v_cvt_pk_bf16_f32 v144, v144, v145
	v_cvt_pk_bf16_f32 v145, v158, v159
	global_store_dwordx2 v[146:147], v[144:145], off
	v_pk_mul_f32 v[158:159], v[72:73], v[132:133] op_sel_hi:[1,0]
	v_pk_mul_f32 v[144:145], v[158:159], v[244:245]
	v_pk_mul_f32 v[158:159], v[74:75], v[132:133] op_sel_hi:[1,0]
	v_cvt_pk_bf16_f32 v144, v144, v145
	v_pk_mul_f32 v[146:147], v[158:159], v[246:247]
	s_nop 0
	v_cvt_pk_bf16_f32 v145, v146, v147
	v_lshl_add_u64 v[146:147], v[142:143], 0, v[148:149]
	global_store_dwordx2 v[146:147], v[144:145], off
	v_pk_mul_f32 v[148:149], v[64:65], v[132:133] op_sel_hi:[1,0]
	v_pk_mul_f32 v[144:145], v[148:149], v[248:249]
	v_pk_mul_f32 v[148:149], v[66:67], v[132:133] op_sel_hi:[1,0]
	v_cvt_pk_bf16_f32 v144, v144, v145
	v_pk_mul_f32 v[146:147], v[148:149], v[250:251]
	v_add_u32_e32 v148, 0x80, v130
	v_cvt_pk_bf16_f32 v145, v146, v147
	v_lshl_add_u64 v[146:147], v[142:143], 0, v[150:151]
	ds_read2_b32 v[150:151], v156 offset1:16
	global_store_dwordx2 v[146:147], v[144:145], off
	v_ashrrev_i32_e32 v149, 31, v148
	s_waitcnt lgkmcnt(0)
	v_add_f32_e32 v131, v155, v150
	v_fmamk_f32 v131, v131, 0x3c000000, v160
	v_cmp_gt_f32_e32 vcc, s81, v131
	v_mul_f32_e32 v132, 0x4f800000, v131
	s_nop 0
	v_cndmask_b32_e32 v131, v131, v132, vcc
	v_sqrt_f32_e32 v132, v131
	s_nop 0
	v_add_u32_e32 v144, -1, v132
	v_fma_f32 v145, -v144, v132, v131
	v_cmp_ge_f32_e64 s[4:5], 0, v145
	v_add_u32_e32 v145, 1, v132
	s_nop 0
	v_cndmask_b32_e64 v144, v132, v144, s[4:5]
	v_fma_f32 v132, -v145, v132, v131
	v_cmp_lt_f32_e64 s[4:5], 0, v132
	s_nop 1
	v_cndmask_b32_e64 v132, v144, v145, s[4:5]
	v_mul_f32_e32 v144, 0x37800000, v132
	v_cndmask_b32_e32 v132, v132, v144, vcc
	v_cmp_class_f32_e32 vcc, v131, v161
	s_nop 1
	v_cndmask_b32_e32 v131, v132, v131, vcc
	v_div_scale_f32 v132, s[2:3], v131, v131, 1.0
	v_rcp_f32_e32 v144, v132
	s_nop 0
	v_fma_f32 v145, -v132, v144, 1.0
	v_fmac_f32_e32 v144, v145, v144
	v_div_scale_f32 v145, vcc, 1.0, v131, 1.0
	v_mul_f32_e32 v146, v145, v144
	v_fma_f32 v147, -v132, v146, v145
	v_fmac_f32_e32 v146, v147, v144
	v_fma_f32 v132, -v132, v146, v145
	v_div_fmas_f32 v132, v132, v144, v146
	v_div_fixup_f32 v132, v132, v131, 1.0
	v_pk_mul_f32 v[158:159], v[60:61], v[132:133] op_sel_hi:[1,0]
	v_pk_mul_f32 v[166:167], v[52:53], v[132:133] op_sel_hi:[1,0]
	v_pk_mul_f32 v[144:145], v[236:237], v[158:159]
	s_nop 0
	v_cvt_pk_bf16_f32 v158, v144, v145
	v_pk_mul_f32 v[144:145], v[62:63], v[132:133] op_sel_hi:[1,0]
	s_nop 0
	v_pk_mul_f32 v[144:145], v[238:239], v[144:145]
	s_nop 0
	v_cvt_pk_bf16_f32 v159, v144, v145
	v_lshlrev_b64 v[144:145], 1, v[148:149]
	v_lshl_add_u64 v[146:147], v[128:129], 0, v[144:145]
	global_store_dwordx2 v[146:147], v[158:159], off
	v_add_u32_e32 v158, 0x90, v130
	v_ashrrev_i32_e32 v159, 31, v158
	v_pk_mul_f32 v[146:147], v[166:167], v[240:241]
	s_nop 0
	v_cvt_pk_bf16_f32 v166, v146, v147
	v_pk_mul_f32 v[146:147], v[54:55], v[132:133] op_sel_hi:[1,0]
	s_nop 0
	v_pk_mul_f32 v[146:147], v[146:147], v[242:243]
	s_nop 0
	v_cvt_pk_bf16_f32 v167, v146, v147
	v_lshlrev_b64 v[146:147], 1, v[158:159]
	v_lshl_add_u64 v[148:149], v[128:129], 0, v[146:147]
	global_store_dwordx2 v[148:149], v[166:167], off
	v_add_u32_e32 v148, 0xa0, v130
; __device__ __forceinline__ void gemm_tile(const TileDesc& td, char* shm_c, const int wv) {
;     ...
;     #pragma unroll
;     for (int ai = 0; ai < 2; ++ai)
;     #pragma unroll
;     for (int bj = 0; bj < 2; ++bj)
;     #pragma unroll
;     for (int n = 0; n < 2; ++n) {
;       const float tot = ssq[ai][bj][n] + red[((1 - e_wr) * 2 + ai) * 256 + bj * 128 + n * 16 + br_l];
;       const float rstd = 1.0f / sqrtf(tot * (1.0f / 128.f) + EPS);
;       #pragma unroll
;       for (int m = 0; m < 4; ++m) {
;         const float4 g = *(const float4*)(td.aux + m * 16 + ar_l);
;         f32x4 v = acc[ai][bj][m][n];
;         long o = (long)(td.bcol + bj * 128 + n * 16 + br_l) * td.ldo + (td.brow + ai * 128 + m * 16 + ar_l);
;         uint2 pk; pk.x = pack2(v[0] * rstd * g.x, v[1] * rstd * g.y); pk.y = pack2(v[2] * rstd * g.z, v[3] * rstd * g.w);
;         *(uint2*)(td.outb + o) = pk;
;       }
	v_pk_mul_f32 v[158:159], v[44:45], v[132:133] op_sel_hi:[1,0]
	v_ashrrev_i32_e32 v149, 31, v148
	v_lshlrev_b64 v[148:149], 1, v[148:149]
	v_add_u32_e32 v130, 0xb0, v130
	v_ashrrev_i32_e32 v131, 31, v130
	v_lshlrev_b64 v[130:131], 1, v[130:131]
	v_pk_mul_f32 v[158:159], v[158:159], v[244:245]
	v_pk_mul_f32 v[166:167], v[46:47], v[132:133] op_sel_hi:[1,0]
	v_cvt_pk_bf16_f32 v158, v158, v159
	v_pk_mul_f32 v[166:167], v[166:167], v[246:247]
	s_nop 0
	v_cvt_pk_bf16_f32 v159, v166, v167
	v_lshl_add_u64 v[166:167], v[128:129], 0, v[148:149]
	global_store_dwordx2 v[166:167], v[158:159], off
	v_pk_mul_f32 v[158:159], v[36:37], v[132:133] op_sel_hi:[1,0]
	v_lshl_add_u64 v[128:129], v[128:129], 0, v[130:131]
	v_pk_mul_f32 v[158:159], v[158:159], v[248:249]
	v_pk_mul_f32 v[166:167], v[38:39], v[132:133] op_sel_hi:[1,0]
	v_cvt_pk_bf16_f32 v158, v158, v159
	v_pk_mul_f32 v[166:167], v[166:167], v[250:251]
	s_nop 0
	v_cvt_pk_bf16_f32 v159, v166, v167
	global_store_dwordx2 v[128:129], v[158:159], off
	v_add_f32_e32 v128, v154, v151
	v_fmamk_f32 v128, v128, 0x3c000000, v160
	v_cmp_gt_f32_e32 vcc, s81, v128
	v_mul_f32_e32 v129, 0x4f800000, v128
	s_nop 0
	v_cndmask_b32_e32 v128, v128, v129, vcc
	v_sqrt_f32_e32 v129, v128
	s_nop 0
	v_add_u32_e32 v132, -1, v129
	v_fma_f32 v150, -v132, v129, v128
	v_cmp_ge_f32_e64 s[4:5], 0, v150
	v_add_u32_e32 v150, 1, v129
	s_nop 0
	v_cndmask_b32_e64 v132, v129, v132, s[4:5]
	v_fma_f32 v129, -v150, v129, v128
	v_cmp_lt_f32_e64 s[4:5], 0, v129
	s_nop 1
	v_cndmask_b32_e64 v129, v132, v150, s[4:5]
	v_mul_f32_e32 v132, 0x37800000, v129
	v_cndmask_b32_e32 v129, v129, v132, vcc
	v_cmp_class_f32_e32 vcc, v128, v161
	s_nop 1
	v_cndmask_b32_e32 v128, v129, v128, vcc
	v_div_scale_f32 v129, s[2:3], v128, v128, 1.0
	v_rcp_f32_e32 v132, v129
	s_nop 0
	v_fma_f32 v150, -v129, v132, 1.0
	v_fmac_f32_e32 v132, v150, v132
	v_div_scale_f32 v150, vcc, 1.0, v128, 1.0
	v_mul_f32_e32 v151, v150, v132
	v_fma_f32 v154, -v129, v151, v150
	v_fmac_f32_e32 v151, v154, v132
	v_fma_f32 v129, -v129, v151, v150
	v_div_fmas_f32 v129, v129, v132, v151
	v_div_fixup_f32 v128, v129, v128, 1.0
	v_pk_mul_f32 v[150:151], v[56:57], v[128:129] op_sel_hi:[1,0]
	v_pk_mul_f32 v[154:155], v[58:59], v[128:129] op_sel_hi:[1,0]
	v_pk_mul_f32 v[150:151], v[236:237], v[150:151]
	v_pk_mul_f32 v[154:155], v[238:239], v[154:155]
	v_cvt_pk_bf16_f32 v150, v150, v151
	v_cvt_pk_bf16_f32 v151, v154, v155
	v_lshl_add_u64 v[154:155], v[138:139], 0, v[144:145]
	global_store_dwordx2 v[154:155], v[150:151], off
	v_pk_mul_f32 v[150:151], v[48:49], v[128:129] op_sel_hi:[1,0]
	v_pk_mul_f32 v[154:155], v[50:51], v[128:129] op_sel_hi:[1,0]
	v_pk_mul_f32 v[150:151], v[150:151], v[240:241]
	v_pk_mul_f32 v[154:155], v[154:155], v[242:243]
	v_cvt_pk_bf16_f32 v150, v150, v151
	v_cvt_pk_bf16_f32 v151, v154, v155
	v_lshl_add_u64 v[154:155], v[138:139], 0, v[146:147]
	global_store_dwordx2 v[154:155], v[150:151], off
	v_pk_mul_f32 v[150:151], v[40:41], v[128:129] op_sel_hi:[1,0]
	v_pk_mul_f32 v[154:155], v[42:43], v[128:129] op_sel_hi:[1,0]
	v_pk_mul_f32 v[150:151], v[150:151], v[244:245]
	v_pk_mul_f32 v[154:155], v[154:155], v[246:247]
	v_cvt_pk_bf16_f32 v150, v150, v151
	v_cvt_pk_bf16_f32 v151, v154, v155
	v_lshl_add_u64 v[154:155], v[138:139], 0, v[148:149]
	global_store_dwordx2 v[154:155], v[150:151], off
	v_pk_mul_f32 v[150:151], v[32:33], v[128:129] op_sel_hi:[1,0]
	v_pk_mul_f32 v[128:129], v[34:35], v[128:129] op_sel_hi:[1,0]
	v_pk_mul_f32 v[150:151], v[150:151], v[248:249]
	v_pk_mul_f32 v[128:129], v[128:129], v[250:251]
	v_cvt_pk_bf16_f32 v150, v150, v151
	v_cvt_pk_bf16_f32 v151, v128, v129
	v_lshl_add_u64 v[128:129], v[138:139], 0, v[130:131]
	global_store_dwordx2 v[128:129], v[150:151], off
	ds_read2_b32 v[128:129], v156 offset0:128 offset1:144
	s_waitcnt lgkmcnt(0)
; __device__ __forceinline__ void gemm_tile(const TileDesc& td, char* shm_c, const int wv) {
;     ...
;     #pragma unroll
;     for (int ai = 0; ai < 2; ++ai)
;     #pragma unroll
;     for (int bj = 0; bj < 2; ++bj)
;     #pragma unroll
;     for (int n = 0; n < 2; ++n) {
;       const float tot = ssq[ai][bj][n] + red[((1 - e_wr) * 2 + ai) * 256 + bj * 128 + n * 16 + br_l];
;       const float rstd = 1.0f / sqrtf(tot * (1.0f / 128.f) + EPS);
;       #pragma unroll
;       for (int m = 0; m < 4; ++m) {
;         const float4 g = *(const float4*)(td.aux + m * 16 + ar_l);
;         f32x4 v = acc[ai][bj][m][n];
;         long o = (long)(td.bcol + bj * 128 + n * 16 + br_l) * td.ldo + (td.brow + ai * 128 + m * 16 + ar_l);
;         uint2 pk; pk.x = pack2(v[0] * rstd * g.x, v[1] * rstd * g.y); pk.y = pack2(v[2] * rstd * g.z, v[3] * rstd * g.w);
;         *(uint2*)(td.outb + o) = pk;
;       }
	v_add_f32_e32 v128, v153, v128
	v_fmamk_f32 v128, v128, 0x3c000000, v160
	v_cmp_gt_f32_e32 vcc, s81, v128
	v_mul_f32_e32 v132, 0x4f800000, v128
	s_nop 0
	v_cndmask_b32_e32 v128, v128, v132, vcc
	v_sqrt_f32_e32 v132, v128
	s_nop 0
	v_add_u32_e32 v138, -1, v132
	v_fma_f32 v139, -v138, v132, v128
	v_cmp_ge_f32_e64 s[4:5], 0, v139
	v_add_u32_e32 v139, 1, v132
	s_nop 0
	v_cndmask_b32_e64 v138, v132, v138, s[4:5]
	v_fma_f32 v132, -v139, v132, v128
	v_cmp_lt_f32_e64 s[4:5], 0, v132
	s_nop 1
	v_cndmask_b32_e64 v132, v138, v139, s[4:5]
	v_mul_f32_e32 v138, 0x37800000, v132
	v_cndmask_b32_e32 v132, v132, v138, vcc
	v_cmp_class_f32_e32 vcc, v128, v161
	s_nop 1
	v_cndmask_b32_e32 v128, v132, v128, vcc
	v_div_scale_f32 v132, s[2:3], v128, v128, 1.0
	v_rcp_f32_e32 v138, v132
	s_nop 0
	v_fma_f32 v139, -v132, v138, 1.0
	v_fmac_f32_e32 v138, v139, v138
	v_div_scale_f32 v139, vcc, 1.0, v128, 1.0
	v_mul_f32_e32 v150, v139, v138
	v_fma_f32 v151, -v132, v150, v139
	v_fmac_f32_e32 v150, v151, v138
	v_fma_f32 v132, -v132, v150, v139
	v_div_fmas_f32 v132, v132, v138, v150
	v_div_fixup_f32 v128, v132, v128, 1.0
	v_pk_mul_f32 v[138:139], v[28:29], v[128:129] op_sel_hi:[1,0]
	v_pk_mul_f32 v[150:151], v[30:31], v[128:129] op_sel_hi:[1,0]
	v_pk_mul_f32 v[138:139], v[236:237], v[138:139]
	v_pk_mul_f32 v[150:151], v[238:239], v[150:151]
	v_cvt_pk_bf16_f32 v138, v138, v139
	v_cvt_pk_bf16_f32 v139, v150, v151
	v_lshl_add_u64 v[150:151], v[140:141], 0, v[144:145]
	global_store_dwordx2 v[150:151], v[138:139], off
	v_pk_mul_f32 v[138:139], v[20:21], v[128:129] op_sel_hi:[1,0]
	v_pk_mul_f32 v[150:151], v[22:23], v[128:129] op_sel_hi:[1,0]
	v_pk_mul_f32 v[138:139], v[138:139], v[240:241]
	v_pk_mul_f32 v[150:151], v[150:151], v[242:243]
	v_cvt_pk_bf16_f32 v138, v138, v139
	v_cvt_pk_bf16_f32 v139, v150, v151
	v_lshl_add_u64 v[150:151], v[140:141], 0, v[146:147]
	global_store_dwordx2 v[150:151], v[138:139], off
	v_pk_mul_f32 v[138:139], v[12:13], v[128:129] op_sel_hi:[1,0]
	v_pk_mul_f32 v[150:151], v[14:15], v[128:129] op_sel_hi:[1,0]
	v_pk_mul_f32 v[138:139], v[138:139], v[244:245]
	v_pk_mul_f32 v[150:151], v[150:151], v[246:247]
	v_cvt_pk_bf16_f32 v138, v138, v139
	v_cvt_pk_bf16_f32 v139, v150, v151
	v_lshl_add_u64 v[150:151], v[140:141], 0, v[148:149]
	global_store_dwordx2 v[150:151], v[138:139], off
	v_pk_mul_f32 v[138:139], v[4:5], v[128:129] op_sel_hi:[1,0]
	v_pk_mul_f32 v[150:151], v[6:7], v[128:129] op_sel_hi:[1,0]
	v_add_f32_e32 v128, v152, v129
	v_fmamk_f32 v128, v128, 0x3c000000, v160
	v_cmp_gt_f32_e32 vcc, s81, v128
	v_mul_f32_e32 v129, 0x4f800000, v128
	v_lshl_add_u64 v[140:141], v[140:141], 0, v[130:131]
	v_cndmask_b32_e32 v128, v128, v129, vcc
	v_sqrt_f32_e32 v129, v128
	v_pk_mul_f32 v[138:139], v[138:139], v[248:249]
	v_pk_mul_f32 v[150:151], v[150:151], v[250:251]
	v_cvt_pk_bf16_f32 v138, v138, v139
	v_cvt_pk_bf16_f32 v139, v150, v151
	v_add_u32_e32 v132, -1, v129
	global_store_dwordx2 v[140:141], v[138:139], off
	v_fma_f32 v138, -v132, v129, v128
	v_cmp_ge_f32_e64 s[4:5], 0, v138
	v_add_u32_e32 v138, 1, v129
	s_nop 0
	v_cndmask_b32_e64 v132, v129, v132, s[4:5]
	v_fma_f32 v129, -v138, v129, v128
	v_cmp_lt_f32_e64 s[4:5], 0, v129
	s_nop 1
	v_cndmask_b32_e64 v129, v132, v138, s[4:5]
	v_mul_f32_e32 v132, 0x37800000, v129
	v_cndmask_b32_e32 v129, v129, v132, vcc
	v_cmp_class_f32_e32 vcc, v128, v161
	s_mov_b64 s[4:5], 0
	s_nop 0
	v_cndmask_b32_e32 v128, v129, v128, vcc
	v_div_scale_f32 v129, s[2:3], v128, v128, 1.0
	v_rcp_f32_e32 v132, v129
	s_nop 0
	v_fma_f32 v138, -v129, v132, 1.0
	v_fmac_f32_e32 v132, v138, v132
	v_div_scale_f32 v138, vcc, 1.0, v128, 1.0
	v_mul_f32_e32 v139, v138, v132
	v_fma_f32 v140, -v129, v139, v138
	v_fmac_f32_e32 v139, v140, v132
	v_fma_f32 v129, -v129, v139, v138
	v_div_fmas_f32 v129, v129, v132, v139
	v_div_fixup_f32 v128, v129, v128, 1.0
	v_pk_mul_f32 v[150:151], v[24:25], v[128:129] op_sel_hi:[1,0]
	v_pk_mul_f32 v[138:139], v[236:237], v[150:151]
	v_pk_mul_f32 v[150:151], v[26:27], v[128:129] op_sel_hi:[1,0]
	v_cvt_pk_bf16_f32 v138, v138, v139
	v_pk_mul_f32 v[140:141], v[238:239], v[150:151]
	s_nop 0
	v_cvt_pk_bf16_f32 v139, v140, v141
	v_lshl_add_u64 v[140:141], v[142:143], 0, v[144:145]
	global_store_dwordx2 v[140:141], v[138:139], off
	v_pk_mul_f32 v[144:145], v[16:17], v[128:129] op_sel_hi:[1,0]
	v_pk_mul_f32 v[138:139], v[144:145], v[240:241]
	v_pk_mul_f32 v[144:145], v[18:19], v[128:129] op_sel_hi:[1,0]
	v_cvt_pk_bf16_f32 v138, v138, v139
	v_pk_mul_f32 v[140:141], v[144:145], v[242:243]
	v_pk_mul_f32 v[144:145], v[8:9], v[128:129] op_sel_hi:[1,0]
	v_cvt_pk_bf16_f32 v139, v140, v141
	v_lshl_add_u64 v[140:141], v[142:143], 0, v[146:147]
	global_store_dwordx2 v[140:141], v[138:139], off
	v_pk_mul_f32 v[138:139], v[144:145], v[244:245]
	v_pk_mul_f32 v[144:145], v[10:11], v[128:129] op_sel_hi:[1,0]
	v_cvt_pk_bf16_f32 v138, v138, v139
	v_pk_mul_f32 v[140:141], v[144:145], v[246:247]
	v_pk_mul_f32 v[144:145], v[0:1], v[128:129] op_sel_hi:[1,0]
	v_cvt_pk_bf16_f32 v139, v140, v141
	v_lshl_add_u64 v[140:141], v[142:143], 0, v[148:149]
	global_store_dwordx2 v[140:141], v[138:139], off
	v_pk_mul_f32 v[128:129], v[2:3], v[128:129] op_sel_hi:[1,0]
	v_pk_mul_f32 v[138:139], v[144:145], v[248:249]
	v_pk_mul_f32 v[128:129], v[128:129], v[250:251]
	v_cvt_pk_bf16_f32 v138, v138, v139
	v_cvt_pk_bf16_f32 v139, v128, v129
	v_lshl_add_u64 v[128:129], v[142:143], 0, v[130:131]
	global_store_dwordx2 v[128:129], v[138:139], off
